# in-proj K-loop: SGPR-base LDS-DMA form (no 64-bit VALU address adds), no setprio flips; setprio flips removed in other GEMM loops
# speedup vs baseline: 1.0079x; 1.0079x over previous
;     __device__ bool next(int i, Unit& u) const { const int t = c + i * nb; if (t >= 128) return false; u.pm = t & 31; u.pn = 88 + (t >> 5); return true; }
; #define PG8_STAGE(bufoff, gbase, voff) do { _Pragma("unroll") for (int _i = 0; _i < 2; ++_i) \
;         __builtin_amdgcn_global_load_lds((const unsigned*)((const char*)(gbase) + (voff)[_i]), (PG8_LAS unsigned*)(lds + (bufoff) + ldsw + _i * 8192), 16, 0, 0); } while (0)
; #define PG8_LDA(dst, b, h) do { _Pragma("unroll") for (int m = 0; m < 4; ++m) _Pragma("unroll") for (int k = 0; k < 2; ++k) dst[m][k] = *(const PG8_LAS bf16x8*)(lds + PG8_SA(b, h) + aoff + m * 2048 + k * 1024); } while (0)
; #define PG8_LDB(dst, b, h) do { _Pragma("unroll") for (int n = 0; n < 2; ++n) _Pragma("unroll") for (int k = 0; k < 2; ++k) dst[n][k] = *(const PG8_LAS bf16x8*)(lds + PG8_SB(b, h) + boff + n * 2048 + k * 1024); } while (0)
; #define PG8_MMA(ai, bj, At, Bt) do { __builtin_amdgcn_s_setprio(1); _Pragma("unroll") for (int m = 0; m < 4; ++m) _Pragma("unroll") for (int n = 0; n < 2; ++n) _Pragma("unroll") for (int k = 0; k < 2; ++k) \
;         acc[ai][bj][m][n] = __builtin_amdgcn_mfma_f32_16x16x32_bf16(Bt[n][k], At[m][k], acc[ai][bj][m][n], 0, 0, 0); __builtin_amdgcn_s_setprio(0); } while (0)
; #define PG8_BAR __builtin_amdgcn_s_barrier()
; template <class Epi, class Sched, bool ALIGN_EPI = false, bool SP2 = false>
; __device__ __forceinline__ void gemm_phase(PG8_LAS unsigned char* lds, const Gemm g, const Sched& S, const Epi& E) {
;     ...
;         const bool has_next = S.next(ui + 1, nxt);
;         const char* nA = has_next ? (const char*)g.A + (size_t)nxt.pm * tstep : cA; const char* nB = has_next ? (const char*)g.Bt + (size_t)nxt.pn * tstep : cB;
;         for (int t = 0; t < nt; t += 2) {
;             const bool last = (t == nt - 2);
;             const char* a1 = cA + (size_t)(t + 1) * kstep;
;             const char* a2 = last ? nA : cA + (size_t)(t + 2) * kstep; const char* b2 = last ? nB : cB + (size_t)(t + 2) * kstep;
;             const char* a3 = a2 + kstep; const char* b3 = b2 + kstep;
;             if (last && has_next) S.a_ready(nxt);
;             if constexpr (SP2) {
;             PG8_LDB(B0, 0, 0); PG8_LDB(B1, 0, 1); PG8_SCHED; PG8_LDA(At, 0, 0); PG8_STAGE(PG8_SA(1, 1), a1 + hstep, voffA);
;             PG8_WAIT_V(8); PG8_WAIT_L(0); PG8_BAR; PG8_MMA(0, 0, At, B0); PG8_MMA(0, 1, At, B1); PG8_BAR; PG8_SCHED;
.LBB0_227:
	s_ashr_i32 s17, s16, 31
	s_lshl_b64 s[18:19], s[16:17], 20
	s_add_u32 s18, s24, s18
	s_addc_u32 s19, s25, s19
	s_and_b64 s[20:21], s[6:7], exec
	s_cselect_b32 s17, s19, s5
	s_cselect_b32 s40, s18, s4
	s_ashr_i32 s15, s14, 31
	s_lshl_b64 s[20:21], s[14:15], 20
	s_add_u32 s20, s26, s20
	s_addc_u32 s21, s27, s21
	s_and_b64 s[22:23], s[6:7], exec
	s_cselect_b32 s15, s21, s1
	s_cselect_b32 s41, s20, s0
	s_add_u32 s22, s4, 0x80080
	s_addc_u32 s23, s5, 0
	s_add_u32 s42, s0, 0x100
	v_mov_b32_e32 v2, 0
	s_addc_u32 s43, s1, 0
	s_mov_b32 s47, -2
	v_mov_b32_e32 v3, v2
	v_mov_b32_e32 v4, v2
	v_mov_b32_e32 v5, v2
	v_mov_b32_e32 v6, v2
	v_mov_b32_e32 v7, v2
	v_mov_b32_e32 v8, v2
	v_mov_b32_e32 v9, v2
	v_mov_b32_e32 v14, v2
	v_mov_b32_e32 v15, v2
	v_mov_b32_e32 v16, v2
	v_mov_b32_e32 v17, v2
	v_mov_b32_e32 v22, v2
	v_mov_b32_e32 v23, v2
	v_mov_b32_e32 v24, v2
	v_mov_b32_e32 v25, v2
	v_mov_b32_e32 v30, v2
	v_mov_b32_e32 v31, v2
	v_mov_b32_e32 v32, v2
	v_mov_b32_e32 v33, v2
	v_mov_b32_e32 v38, v2
	v_mov_b32_e32 v39, v2
	v_mov_b32_e32 v40, v2
	v_mov_b32_e32 v41, v2
	v_mov_b32_e32 v46, v2
	v_mov_b32_e32 v47, v2
	v_mov_b32_e32 v48, v2
	v_mov_b32_e32 v49, v2
	v_mov_b32_e32 v54, v2
	v_mov_b32_e32 v55, v2
	v_mov_b32_e32 v56, v2
	v_mov_b32_e32 v57, v2
	v_mov_b32_e32 v10, v2
	v_mov_b32_e32 v11, v2
	v_mov_b32_e32 v12, v2
	v_mov_b32_e32 v13, v2
	v_mov_b32_e32 v18, v2
	v_mov_b32_e32 v19, v2
	v_mov_b32_e32 v20, v2
	v_mov_b32_e32 v21, v2
	v_mov_b32_e32 v26, v2
	v_mov_b32_e32 v27, v2
	v_mov_b32_e32 v28, v2
	v_mov_b32_e32 v29, v2
	v_mov_b32_e32 v34, v2
	v_mov_b32_e32 v35, v2
	v_mov_b32_e32 v36, v2
	v_mov_b32_e32 v37, v2
	v_mov_b32_e32 v42, v2
	v_mov_b32_e32 v43, v2
	v_mov_b32_e32 v44, v2
	v_mov_b32_e32 v45, v2
	v_mov_b32_e32 v50, v2
	v_mov_b32_e32 v51, v2
	v_mov_b32_e32 v52, v2
	v_mov_b32_e32 v53, v2
	v_mov_b32_e32 v58, v2
	v_mov_b32_e32 v59, v2
	v_mov_b32_e32 v60, v2
	v_mov_b32_e32 v61, v2
	v_mov_b32_e32 v62, v2
	v_mov_b32_e32 v63, v2
	v_mov_b32_e32 v64, v2
	v_mov_b32_e32 v65, v2
	v_mov_b32_e32 v66, v2
	v_mov_b32_e32 v67, v2
	v_mov_b32_e32 v68, v2
	v_mov_b32_e32 v69, v2
	v_mov_b32_e32 v70, v2
	v_mov_b32_e32 v71, v2
	v_mov_b32_e32 v72, v2
	v_mov_b32_e32 v73, v2
	v_mov_b32_e32 v78, v2
	v_mov_b32_e32 v79, v2
	v_mov_b32_e32 v80, v2
	v_mov_b32_e32 v81, v2
	v_mov_b32_e32 v86, v2
	v_mov_b32_e32 v87, v2
	v_mov_b32_e32 v88, v2
	v_mov_b32_e32 v89, v2
	v_mov_b32_e32 v94, v2
	v_mov_b32_e32 v95, v2
	v_mov_b32_e32 v96, v2
	v_mov_b32_e32 v97, v2
	v_mov_b32_e32 v102, v2
	v_mov_b32_e32 v103, v2
	v_mov_b32_e32 v104, v2
	v_mov_b32_e32 v105, v2
	v_mov_b32_e32 v110, v2
	v_mov_b32_e32 v111, v2
	v_mov_b32_e32 v112, v2
	v_mov_b32_e32 v113, v2
	v_mov_b32_e32 v118, v2
	v_mov_b32_e32 v119, v2
	v_mov_b32_e32 v120, v2
	v_mov_b32_e32 v121, v2
	v_mov_b32_e32 v74, v2
	v_mov_b32_e32 v75, v2
	v_mov_b32_e32 v76, v2
	v_mov_b32_e32 v77, v2
	v_mov_b32_e32 v82, v2
	v_mov_b32_e32 v83, v2
	v_mov_b32_e32 v84, v2
	v_mov_b32_e32 v85, v2
	v_mov_b32_e32 v90, v2
	v_mov_b32_e32 v91, v2
	v_mov_b32_e32 v92, v2
	v_mov_b32_e32 v93, v2
	v_mov_b32_e32 v98, v2
	v_mov_b32_e32 v99, v2
	v_mov_b32_e32 v100, v2
	v_mov_b32_e32 v101, v2
	v_mov_b32_e32 v106, v2
	v_mov_b32_e32 v107, v2
	v_mov_b32_e32 v108, v2
	v_mov_b32_e32 v109, v2
	v_mov_b32_e32 v114, v2
	v_mov_b32_e32 v115, v2
	v_mov_b32_e32 v116, v2
	v_mov_b32_e32 v117, v2
	v_mov_b32_e32 v122, v2
	v_mov_b32_e32 v123, v2
	v_mov_b32_e32 v124, v2
	v_mov_b32_e32 v125, v2
	v_mov_b32_e32 v126, v2
	v_mov_b32_e32 v127, v2
	v_mov_b32_e32 v128, v2
	v_mov_b32_e32 v129, v2
	v_add_u32_e32 v144, 0x10000, v146
.LBB0_228:
	s_add_u32 s0, s22, 0xfff80080
	s_addc_u32 s1, s23, -1
	s_cmp_eq_u32 s47, 28
	s_cselect_b32 s5, s17, s1
	s_cselect_b32 s4, s40, s0
	s_cselect_b32 s1, s15, s43
	s_cselect_b32 s0, s41, s42
	s_add_u32 s48, s0, 0x80000
	s_addc_u32 s49, s1, 0
	s_add_u32 s98, s0, 0x80
	s_addc_u32 s99, s1, 0
	ds_read_b128 v[148:151], v144 offset:0
	ds_read_b128 v[152:155], v144 offset:1024
	ds_read_b128 v[156:159], v144 offset:2048
	ds_read_b128 v[160:163], v144 offset:3072
	ds_read_b128 v[164:167], v144 offset:16384
	ds_read_b128 v[168:171], v144 offset:17408
	ds_read_b128 v[172:175], v144 offset:18432
	ds_read_b128 v[176:179], v144 offset:19456
	ds_read_b128 v[180:183], v147 offset:0
	ds_read_b128 v[184:187], v147 offset:1024
	ds_read_b128 v[188:191], v147 offset:2048
	ds_read_b128 v[192:195], v147 offset:3072
	ds_read_b128 v[206:209], v147 offset:4096
	ds_read_b128 v[210:213], v147 offset:5120
	ds_read_b128 v[214:217], v147 offset:6144
	ds_read_b128 v[218:221], v147 offset:7168
	s_add_i32 m0, s29, 0xc000
	s_nop 0
	global_load_lds_dwordx4 v138, s[22:23]
	s_add_i32 m0, s29, 0xe000
	s_nop 0
	global_load_lds_dwordx4 v140, s[22:23]
	s_waitcnt vmcnt(8)
	s_waitcnt lgkmcnt(0)
	s_barrier
; #define PG8_STAGE(bufoff, gbase, voff) do { _Pragma("unroll") for (int _i = 0; _i < 2; ++_i) \
;         __builtin_amdgcn_global_load_lds((const unsigned*)((const char*)(gbase) + (voff)[_i]), (PG8_LAS unsigned*)(lds + (bufoff) + ldsw + _i * 8192), 16, 0, 0); } while (0)
; #define PG8_LDA(dst, b, h) do { _Pragma("unroll") for (int m = 0; m < 4; ++m) _Pragma("unroll") for (int k = 0; k < 2; ++k) dst[m][k] = *(const PG8_LAS bf16x8*)(lds + PG8_SA(b, h) + aoff + m * 2048 + k * 1024); } while (0)
; #define PG8_MMA(ai, bj, At, Bt) do { __builtin_amdgcn_s_setprio(1); _Pragma("unroll") for (int m = 0; m < 4; ++m) _Pragma("unroll") for (int n = 0; n < 2; ++n) _Pragma("unroll") for (int k = 0; k < 2; ++k) \
;         acc[ai][bj][m][n] = __builtin_amdgcn_mfma_f32_16x16x32_bf16(Bt[n][k], At[m][k], acc[ai][bj][m][n], 0, 0, 0); __builtin_amdgcn_s_setprio(0); } while (0)
; #define PG8_WAIT_V(n) asm volatile("s_waitcnt vmcnt(" #n ")" ::: "memory")
; #define PG8_WAIT_L(n) asm volatile("s_waitcnt lgkmcnt(" #n ")" ::: "memory")
; #define PG8_BAR __builtin_amdgcn_s_barrier()
; #define PG8_SCHED __builtin_amdgcn_sched_barrier(0)
; template <class Epi, class Sched, bool ALIGN_EPI = false, bool SP2 = false>
; __device__ __forceinline__ void gemm_phase(PG8_LAS unsigned char* lds, const Gemm g, const Sched& S, const Epi& E) {
;     ...
;             PG8_WAIT_V(8); PG8_WAIT_L(0); PG8_BAR; PG8_MMA(0, 0, At, B0); PG8_MMA(0, 1, At, B1); PG8_BAR; PG8_SCHED;
;             PG8_LDA(At, 0, 1); PG8_STAGE(PG8_SB(0, 0), b2, voffB); PG8_STAGE(PG8_SB(0, 1), b2 + hstep, voffB); PG8_STAGE(PG8_SA(0, 0), a2, voffA);
;             PG8_WAIT_V(8); PG8_WAIT_L(0); PG8_BAR; PG8_MMA(1, 0, At, B0); PG8_MMA(1, 1, At, B1); PG8_BAR; PG8_SCHED;
	v_mfma_f32_16x16x32_bf16 v[126:129], v[148:151], v[180:183], v[126:129]
	v_mfma_f32_16x16x32_bf16 v[122:125], v[156:159], v[180:183], v[122:125]
	v_mfma_f32_16x16x32_bf16 v[114:117], v[148:151], v[188:191], v[114:117]
	v_mfma_f32_16x16x32_bf16 v[106:109], v[156:159], v[188:191], v[106:109]
	v_mfma_f32_16x16x32_bf16 v[98:101], v[148:151], v[206:209], v[98:101]
	v_mfma_f32_16x16x32_bf16 v[90:93], v[156:159], v[206:209], v[90:93]
	v_mfma_f32_16x16x32_bf16 v[82:85], v[148:151], v[214:217], v[82:85]
	v_mfma_f32_16x16x32_bf16 v[74:77], v[156:159], v[214:217], v[74:77]
	v_mfma_f32_16x16x32_bf16 v[126:129], v[152:155], v[184:187], v[126:129]
	v_mfma_f32_16x16x32_bf16 v[122:125], v[160:163], v[184:187], v[122:125]
	v_mfma_f32_16x16x32_bf16 v[114:117], v[152:155], v[192:195], v[114:117]
	v_mfma_f32_16x16x32_bf16 v[106:109], v[160:163], v[192:195], v[106:109]
	v_mfma_f32_16x16x32_bf16 v[98:101], v[152:155], v[210:213], v[98:101]
	v_mfma_f32_16x16x32_bf16 v[90:93], v[160:163], v[210:213], v[90:93]
	v_mfma_f32_16x16x32_bf16 v[82:85], v[152:155], v[218:221], v[82:85]
	v_mfma_f32_16x16x32_bf16 v[74:77], v[160:163], v[218:221], v[74:77]
	v_mfma_f32_16x16x32_bf16 v[118:121], v[164:167], v[180:183], v[118:121]
	v_mfma_f32_16x16x32_bf16 v[110:113], v[172:175], v[180:183], v[110:113]
	v_mfma_f32_16x16x32_bf16 v[102:105], v[164:167], v[188:191], v[102:105]
	v_mfma_f32_16x16x32_bf16 v[94:97], v[172:175], v[188:191], v[94:97]
	v_mfma_f32_16x16x32_bf16 v[86:89], v[164:167], v[206:209], v[86:89]
	v_mfma_f32_16x16x32_bf16 v[78:81], v[172:175], v[206:209], v[78:81]
	v_mfma_f32_16x16x32_bf16 v[70:73], v[164:167], v[214:217], v[70:73]
	v_mfma_f32_16x16x32_bf16 v[66:69], v[172:175], v[214:217], v[66:69]
	v_mfma_f32_16x16x32_bf16 v[118:121], v[168:171], v[184:187], v[118:121]
	v_mfma_f32_16x16x32_bf16 v[110:113], v[176:179], v[184:187], v[110:113]
	v_mfma_f32_16x16x32_bf16 v[102:105], v[168:171], v[192:195], v[102:105]
	v_mfma_f32_16x16x32_bf16 v[94:97], v[176:179], v[192:195], v[94:97]
	v_mfma_f32_16x16x32_bf16 v[86:89], v[168:171], v[210:213], v[86:89]
	v_mfma_f32_16x16x32_bf16 v[78:81], v[176:179], v[210:213], v[78:81]
	v_mfma_f32_16x16x32_bf16 v[70:73], v[168:171], v[218:221], v[70:73]
	v_mfma_f32_16x16x32_bf16 v[66:69], v[176:179], v[218:221], v[66:69]
	s_barrier
	ds_read_b128 v[180:183], v147 offset:16384
	ds_read_b128 v[184:187], v147 offset:17408
	ds_read_b128 v[188:191], v147 offset:18432
	ds_read_b128 v[192:195], v147 offset:19456
	ds_read_b128 v[206:209], v147 offset:20480
	ds_read_b128 v[210:213], v147 offset:21504
	ds_read_b128 v[214:217], v147 offset:22528
	ds_read_b128 v[218:221], v147 offset:23552
	s_add_i32 m0, s29, 0x10000
	s_nop 0
	global_load_lds_dwordx4 v0, s[0:1]
	s_add_i32 m0, s29, 0x12000
	s_nop 0
	global_load_lds_dwordx4 v130, s[0:1]
	s_add_i32 m0, s29, 0x14000
	s_nop 0
	global_load_lds_dwordx4 v0, s[48:49]
	s_add_i32 m0, s29, 0x16000
	s_nop 0
	global_load_lds_dwordx4 v130, s[48:49]
	s_add_i32 m0, s29, 0x0
	s_nop 0
	global_load_lds_dwordx4 v134, s[4:5]
	s_add_i32 m0, s29, 0x2000
	s_nop 0
	global_load_lds_dwordx4 v132, s[4:5]
	s_waitcnt vmcnt(8)
	s_waitcnt lgkmcnt(0)
	s_barrier
	v_mfma_f32_16x16x32_bf16 v[62:65], v[148:151], v[180:183], v[62:65]
	v_mfma_f32_16x16x32_bf16 v[58:61], v[156:159], v[180:183], v[58:61]
	v_mfma_f32_16x16x32_bf16 v[50:53], v[148:151], v[188:191], v[50:53]
	v_mfma_f32_16x16x32_bf16 v[42:45], v[156:159], v[188:191], v[42:45]
	v_mfma_f32_16x16x32_bf16 v[34:37], v[148:151], v[206:209], v[34:37]
	v_mfma_f32_16x16x32_bf16 v[26:29], v[156:159], v[206:209], v[26:29]
	v_mfma_f32_16x16x32_bf16 v[18:21], v[148:151], v[214:217], v[18:21]
	v_mfma_f32_16x16x32_bf16 v[10:13], v[156:159], v[214:217], v[10:13]
	v_mfma_f32_16x16x32_bf16 v[62:65], v[152:155], v[184:187], v[62:65]
	v_mfma_f32_16x16x32_bf16 v[58:61], v[160:163], v[184:187], v[58:61]
	v_mfma_f32_16x16x32_bf16 v[50:53], v[152:155], v[192:195], v[50:53]
	v_mfma_f32_16x16x32_bf16 v[42:45], v[160:163], v[192:195], v[42:45]
	v_mfma_f32_16x16x32_bf16 v[34:37], v[152:155], v[210:213], v[34:37]
	v_mfma_f32_16x16x32_bf16 v[26:29], v[160:163], v[210:213], v[26:29]
	v_mfma_f32_16x16x32_bf16 v[18:21], v[152:155], v[218:221], v[18:21]
	v_mfma_f32_16x16x32_bf16 v[10:13], v[160:163], v[218:221], v[10:13]
	v_mfma_f32_16x16x32_bf16 v[54:57], v[164:167], v[180:183], v[54:57]
	v_mfma_f32_16x16x32_bf16 v[46:49], v[172:175], v[180:183], v[46:49]
	v_mfma_f32_16x16x32_bf16 v[38:41], v[164:167], v[188:191], v[38:41]
	v_mfma_f32_16x16x32_bf16 v[30:33], v[172:175], v[188:191], v[30:33]
	v_mfma_f32_16x16x32_bf16 v[22:25], v[164:167], v[206:209], v[22:25]
	v_mfma_f32_16x16x32_bf16 v[14:17], v[172:175], v[206:209], v[14:17]
	v_mfma_f32_16x16x32_bf16 v[6:9], v[164:167], v[214:217], v[6:9]
	v_mfma_f32_16x16x32_bf16 v[2:5], v[172:175], v[214:217], v[2:5]
	v_mfma_f32_16x16x32_bf16 v[54:57], v[168:171], v[184:187], v[54:57]
	v_mfma_f32_16x16x32_bf16 v[46:49], v[176:179], v[184:187], v[46:49]
	v_mfma_f32_16x16x32_bf16 v[38:41], v[168:171], v[192:195], v[38:41]
	v_mfma_f32_16x16x32_bf16 v[30:33], v[176:179], v[192:195], v[30:33]
	v_mfma_f32_16x16x32_bf16 v[22:25], v[168:171], v[210:213], v[22:25]
	v_mfma_f32_16x16x32_bf16 v[14:17], v[176:179], v[210:213], v[14:17]
	v_mfma_f32_16x16x32_bf16 v[6:9], v[168:171], v[218:221], v[6:9]
	v_mfma_f32_16x16x32_bf16 v[2:5], v[176:179], v[218:221], v[2:5]
	s_barrier
; #define PG8_STAGE(bufoff, gbase, voff) do { _Pragma("unroll") for (int _i = 0; _i < 2; ++_i) \
;         __builtin_amdgcn_global_load_lds((const unsigned*)((const char*)(gbase) + (voff)[_i]), (PG8_LAS unsigned*)(lds + (bufoff) + ldsw + _i * 8192), 16, 0, 0); } while (0)
; #define PG8_LDA(dst, b, h) do { _Pragma("unroll") for (int m = 0; m < 4; ++m) _Pragma("unroll") for (int k = 0; k < 2; ++k) dst[m][k] = *(const PG8_LAS bf16x8*)(lds + PG8_SA(b, h) + aoff + m * 2048 + k * 1024); } while (0)
; #define PG8_LDB(dst, b, h) do { _Pragma("unroll") for (int n = 0; n < 2; ++n) _Pragma("unroll") for (int k = 0; k < 2; ++k) dst[n][k] = *(const PG8_LAS bf16x8*)(lds + PG8_SB(b, h) + boff + n * 2048 + k * 1024); } while (0)
; #define PG8_MMA(ai, bj, At, Bt) do { __builtin_amdgcn_s_setprio(1); _Pragma("unroll") for (int m = 0; m < 4; ++m) _Pragma("unroll") for (int n = 0; n < 2; ++n) _Pragma("unroll") for (int k = 0; k < 2; ++k) \
;         acc[ai][bj][m][n] = __builtin_amdgcn_mfma_f32_16x16x32_bf16(Bt[n][k], At[m][k], acc[ai][bj][m][n], 0, 0, 0); __builtin_amdgcn_s_setprio(0); } while (0)
; #define PG8_WAIT_V(n) asm volatile("s_waitcnt vmcnt(" #n ")" ::: "memory")
; #define PG8_WAIT_L(n) asm volatile("s_waitcnt lgkmcnt(" #n ")" ::: "memory")
; #define PG8_BAR __builtin_amdgcn_s_barrier()
; #define PG8_SCHED __builtin_amdgcn_sched_barrier(0)
; template <class Epi, class Sched, bool ALIGN_EPI = false, bool SP2 = false>
; __device__ __forceinline__ void gemm_phase(PG8_LAS unsigned char* lds, const Gemm g, const Sched& S, const Epi& E) {
;     ...
;         for (int t = 0; t < nt; t += 2) {
;     ...
;             PG8_LDB(B0, 1, 0); PG8_LDB(B1, 1, 1); PG8_SCHED; PG8_LDA(At, 1, 0); PG8_STAGE(PG8_SA(0, 1), a2 + hstep, voffA);
;             PG8_WAIT_V(8); PG8_WAIT_L(0); PG8_BAR; PG8_MMA(0, 0, At, B0); PG8_MMA(0, 1, At, B1); PG8_BAR; PG8_SCHED;
;             PG8_LDA(At, 1, 1); PG8_STAGE(PG8_SB(1, 0), b3, voffB); PG8_STAGE(PG8_SB(1, 1), b3 + hstep, voffB); PG8_STAGE(PG8_SA(1, 0), a3, voffA);
;             PG8_WAIT_V(8); PG8_WAIT_L(0); PG8_BAR; PG8_MMA(1, 0, At, B0); PG8_MMA(1, 1, At, B1); PG8_BAR; PG8_SCHED;
	s_add_u32 s4, s4, 0x80000
	s_addc_u32 s5, s5, 0
	s_add_u32 s0, s0, 0x80080
	s_addc_u32 s1, s1, 0
	ds_read_b128 v[148:151], v144 offset:32768
	ds_read_b128 v[152:155], v144 offset:33792
	ds_read_b128 v[156:159], v144 offset:34816
	ds_read_b128 v[160:163], v144 offset:35840
	ds_read_b128 v[164:167], v144 offset:49152
	ds_read_b128 v[168:171], v144 offset:50176
	ds_read_b128 v[172:175], v144 offset:51200
	ds_read_b128 v[176:179], v144 offset:52224
	ds_read_b128 v[180:183], v147 offset:32768
	ds_read_b128 v[184:187], v147 offset:33792
	ds_read_b128 v[188:191], v147 offset:34816
	ds_read_b128 v[192:195], v147 offset:35840
	ds_read_b128 v[206:209], v147 offset:36864
	ds_read_b128 v[210:213], v147 offset:37888
	ds_read_b128 v[214:217], v147 offset:38912
	ds_read_b128 v[218:221], v147 offset:39936
	s_add_i32 m0, s29, 0x4000
	s_nop 0
	global_load_lds_dwordx4 v134, s[4:5]
	s_add_i32 m0, s29, 0x6000
	s_nop 0
	global_load_lds_dwordx4 v132, s[4:5]
	s_waitcnt vmcnt(8)
	s_waitcnt lgkmcnt(0)
	s_barrier
	v_mfma_f32_16x16x32_bf16 v[126:129], v[148:151], v[180:183], v[126:129]
	v_mfma_f32_16x16x32_bf16 v[122:125], v[156:159], v[180:183], v[122:125]
	v_mfma_f32_16x16x32_bf16 v[114:117], v[148:151], v[188:191], v[114:117]
	v_mfma_f32_16x16x32_bf16 v[106:109], v[156:159], v[188:191], v[106:109]
	v_mfma_f32_16x16x32_bf16 v[98:101], v[148:151], v[206:209], v[98:101]
	v_mfma_f32_16x16x32_bf16 v[90:93], v[156:159], v[206:209], v[90:93]
	v_mfma_f32_16x16x32_bf16 v[82:85], v[148:151], v[214:217], v[82:85]
	v_mfma_f32_16x16x32_bf16 v[74:77], v[156:159], v[214:217], v[74:77]
	v_mfma_f32_16x16x32_bf16 v[126:129], v[152:155], v[184:187], v[126:129]
	v_mfma_f32_16x16x32_bf16 v[122:125], v[160:163], v[184:187], v[122:125]
	v_mfma_f32_16x16x32_bf16 v[114:117], v[152:155], v[192:195], v[114:117]
	v_mfma_f32_16x16x32_bf16 v[106:109], v[160:163], v[192:195], v[106:109]
	v_mfma_f32_16x16x32_bf16 v[98:101], v[152:155], v[210:213], v[98:101]
	v_mfma_f32_16x16x32_bf16 v[90:93], v[160:163], v[210:213], v[90:93]
	v_mfma_f32_16x16x32_bf16 v[82:85], v[152:155], v[218:221], v[82:85]
	v_mfma_f32_16x16x32_bf16 v[74:77], v[160:163], v[218:221], v[74:77]
	v_mfma_f32_16x16x32_bf16 v[118:121], v[164:167], v[180:183], v[118:121]
	v_mfma_f32_16x16x32_bf16 v[110:113], v[172:175], v[180:183], v[110:113]
	v_mfma_f32_16x16x32_bf16 v[102:105], v[164:167], v[188:191], v[102:105]
	v_mfma_f32_16x16x32_bf16 v[94:97], v[172:175], v[188:191], v[94:97]
	v_mfma_f32_16x16x32_bf16 v[86:89], v[164:167], v[206:209], v[86:89]
	v_mfma_f32_16x16x32_bf16 v[78:81], v[172:175], v[206:209], v[78:81]
	v_mfma_f32_16x16x32_bf16 v[70:73], v[164:167], v[214:217], v[70:73]
	v_mfma_f32_16x16x32_bf16 v[66:69], v[172:175], v[214:217], v[66:69]
	v_mfma_f32_16x16x32_bf16 v[118:121], v[168:171], v[184:187], v[118:121]
	v_mfma_f32_16x16x32_bf16 v[110:113], v[176:179], v[184:187], v[110:113]
	v_mfma_f32_16x16x32_bf16 v[102:105], v[168:171], v[192:195], v[102:105]
	v_mfma_f32_16x16x32_bf16 v[94:97], v[176:179], v[192:195], v[94:97]
	v_mfma_f32_16x16x32_bf16 v[86:89], v[168:171], v[210:213], v[86:89]
	v_mfma_f32_16x16x32_bf16 v[78:81], v[176:179], v[210:213], v[78:81]
	v_mfma_f32_16x16x32_bf16 v[70:73], v[168:171], v[218:221], v[70:73]
	v_mfma_f32_16x16x32_bf16 v[66:69], v[176:179], v[218:221], v[66:69]
	s_barrier
	s_add_u32 s4, s4, 0xfff80080
	s_addc_u32 s5, s5, -1
	ds_read_b128 v[180:183], v147 offset:49152
	ds_read_b128 v[184:187], v147 offset:50176
	ds_read_b128 v[188:191], v147 offset:51200
	ds_read_b128 v[192:195], v147 offset:52224
	ds_read_b128 v[206:209], v147 offset:53248
	ds_read_b128 v[210:213], v147 offset:54272
	ds_read_b128 v[214:217], v147 offset:55296
	ds_read_b128 v[218:221], v147 offset:56320
	s_add_i32 m0, s29, 0x18000
	s_nop 0
	global_load_lds_dwordx4 v0, s[98:99]
	s_add_i32 m0, s29, 0x1a000
	s_nop 0
	global_load_lds_dwordx4 v130, s[98:99]
	s_add_i32 m0, s29, 0x1c000
	s_nop 0
	global_load_lds_dwordx4 v0, s[0:1]
	s_add_i32 m0, s29, 0x1e000
	s_nop 0
	global_load_lds_dwordx4 v130, s[0:1]
	s_add_i32 m0, s29, 0x8000
	s_nop 0
	global_load_lds_dwordx4 v134, s[4:5]
	s_add_i32 m0, s29, 0xa000
	s_nop 0
	global_load_lds_dwordx4 v132, s[4:5]
	s_waitcnt vmcnt(8)
	s_waitcnt lgkmcnt(0)
	s_barrier
	v_mfma_f32_16x16x32_bf16 v[62:65], v[148:151], v[180:183], v[62:65]
	v_mfma_f32_16x16x32_bf16 v[58:61], v[156:159], v[180:183], v[58:61]
	v_mfma_f32_16x16x32_bf16 v[50:53], v[148:151], v[188:191], v[50:53]
	v_mfma_f32_16x16x32_bf16 v[42:45], v[156:159], v[188:191], v[42:45]
	v_mfma_f32_16x16x32_bf16 v[34:37], v[148:151], v[206:209], v[34:37]
	v_mfma_f32_16x16x32_bf16 v[26:29], v[156:159], v[206:209], v[26:29]
	v_mfma_f32_16x16x32_bf16 v[18:21], v[148:151], v[214:217], v[18:21]
	v_mfma_f32_16x16x32_bf16 v[10:13], v[156:159], v[214:217], v[10:13]
	v_mfma_f32_16x16x32_bf16 v[62:65], v[152:155], v[184:187], v[62:65]
	v_mfma_f32_16x16x32_bf16 v[58:61], v[160:163], v[184:187], v[58:61]
	v_mfma_f32_16x16x32_bf16 v[50:53], v[152:155], v[192:195], v[50:53]
	v_mfma_f32_16x16x32_bf16 v[42:45], v[160:163], v[192:195], v[42:45]
	v_mfma_f32_16x16x32_bf16 v[34:37], v[152:155], v[210:213], v[34:37]
	v_mfma_f32_16x16x32_bf16 v[26:29], v[160:163], v[210:213], v[26:29]
	v_mfma_f32_16x16x32_bf16 v[18:21], v[152:155], v[218:221], v[18:21]
	v_mfma_f32_16x16x32_bf16 v[10:13], v[160:163], v[218:221], v[10:13]
	v_mfma_f32_16x16x32_bf16 v[54:57], v[164:167], v[180:183], v[54:57]
	v_mfma_f32_16x16x32_bf16 v[46:49], v[172:175], v[180:183], v[46:49]
	v_mfma_f32_16x16x32_bf16 v[38:41], v[164:167], v[188:191], v[38:41]
	v_mfma_f32_16x16x32_bf16 v[30:33], v[172:175], v[188:191], v[30:33]
	v_mfma_f32_16x16x32_bf16 v[22:25], v[164:167], v[206:209], v[22:25]
	v_mfma_f32_16x16x32_bf16 v[14:17], v[172:175], v[206:209], v[14:17]
	v_mfma_f32_16x16x32_bf16 v[6:9], v[164:167], v[214:217], v[6:9]
	v_mfma_f32_16x16x32_bf16 v[2:5], v[172:175], v[214:217], v[2:5]
	v_mfma_f32_16x16x32_bf16 v[54:57], v[168:171], v[184:187], v[54:57]
	v_mfma_f32_16x16x32_bf16 v[46:49], v[176:179], v[184:187], v[46:49]
	v_mfma_f32_16x16x32_bf16 v[38:41], v[168:171], v[192:195], v[38:41]
	v_mfma_f32_16x16x32_bf16 v[30:33], v[176:179], v[192:195], v[30:33]
	v_mfma_f32_16x16x32_bf16 v[22:25], v[168:171], v[210:213], v[22:25]
	v_mfma_f32_16x16x32_bf16 v[14:17], v[176:179], v[210:213], v[14:17]
	v_mfma_f32_16x16x32_bf16 v[6:9], v[168:171], v[218:221], v[6:9]
	v_mfma_f32_16x16x32_bf16 v[2:5], v[176:179], v[218:221], v[2:5]
	s_barrier
	s_add_i32 s47, s47, 2
	s_add_u32 s22, s22, 0x100
	s_addc_u32 s23, s23, 0
	s_add_u32 s42, s42, 0x100
	s_addc_u32 s43, s43, 0
	s_cmp_gt_u32 s47, 29
	s_cbranch_scc0 .LBB0_228
	s_and_b64 vcc, exec, s[12:13]
	s_cbranch_vccz .LBB0_231
	s_barrier

; __global__ void __launch_bounds__(512, 2) fwd_mega(Args a) {
	.amdhsa_kernel _Z8fwd_mega4Args
		.amdhsa_group_segment_fixed_size 0
		.amdhsa_private_segment_fixed_size 0
		.amdhsa_kernarg_size 392
		.amdhsa_user_sgpr_count 2
		.amdhsa_user_sgpr_dispatch_ptr 0
		.amdhsa_user_sgpr_queue_ptr 0
		.amdhsa_user_sgpr_kernarg_segment_ptr 1
		.amdhsa_user_sgpr_dispatch_id 0
		.amdhsa_user_sgpr_kernarg_preload_length 0
		.amdhsa_user_sgpr_kernarg_preload_offset 0
		.amdhsa_user_sgpr_private_segment_size 0
		.amdhsa_uses_dynamic_stack 0
		.amdhsa_enable_private_segment 0
		.amdhsa_system_sgpr_workgroup_id_x 1
		.amdhsa_system_sgpr_workgroup_id_y 0
		.amdhsa_system_sgpr_workgroup_id_z 0
		.amdhsa_system_sgpr_workgroup_info 0
		.amdhsa_system_vgpr_workitem_id 2
		.amdhsa_next_free_vgpr 255
		.amdhsa_next_free_sgpr 102
		.amdhsa_accum_offset 256
		.amdhsa_reserve_vcc 1
		.amdhsa_float_round_mode_32 0
		.amdhsa_float_round_mode_16_64 0
		.amdhsa_float_denorm_mode_32 3
		.amdhsa_float_denorm_mode_16_64 3
		.amdhsa_dx10_clamp 1
		.amdhsa_ieee_mode 1
		.amdhsa_fp16_overflow 0
		.amdhsa_tg_split 0
		.amdhsa_exception_fp_ieee_invalid_op 0
		.amdhsa_exception_fp_denorm_src 0
		.amdhsa_exception_fp_ieee_div_zero 0
		.amdhsa_exception_fp_ieee_overflow 0
		.amdhsa_exception_fp_ieee_underflow 0
		.amdhsa_exception_fp_ieee_inexact 0
		.amdhsa_exception_int_div_zero 0
	.end_amdhsa_kernel

; __global__ void __launch_bounds__(512, 2) fwd_mega(Args a) {
amdhsa.kernels:
  - .agpr_count:     0
    .args:
      - .offset:         0
        .size:           136
        .value_kind:     by_value
      - .offset:         136
        .size:           4
        .value_kind:     hidden_block_count_x
      - .offset:         140
        .size:           4
        .value_kind:     hidden_block_count_y
      - .offset:         144
        .size:           4
        .value_kind:     hidden_block_count_z
      - .offset:         148
        .size:           2
        .value_kind:     hidden_group_size_x
      - .offset:         150
        .size:           2
        .value_kind:     hidden_group_size_y
      - .offset:         152
        .size:           2
        .value_kind:     hidden_group_size_z
      - .offset:         154
        .size:           2
        .value_kind:     hidden_remainder_x
      - .offset:         156
        .size:           2
        .value_kind:     hidden_remainder_y
      - .offset:         158
        .size:           2
        .value_kind:     hidden_remainder_z
      - .offset:         176
        .size:           8
        .value_kind:     hidden_global_offset_x
      - .offset:         184
        .size:           8
        .value_kind:     hidden_global_offset_y
      - .offset:         192
        .size:           8
        .value_kind:     hidden_global_offset_z
      - .offset:         200
        .size:           2
        .value_kind:     hidden_grid_dims
      - .offset:         224
        .size:           8
        .value_kind:     hidden_multigrid_sync_arg
      - .offset:         256
        .size:           4
        .value_kind:     hidden_dynamic_lds_size
    .group_segment_fixed_size: 0
    .kernarg_segment_align: 8
    .kernarg_segment_size: 392
    .language:       OpenCL C
    .language_version:
      - 2
      - 0
    .max_flat_workgroup_size: 512
    .name:           _Z8fwd_mega4Args
    .private_segment_fixed_size: 0
    .sgpr_count:     108
    .sgpr_spill_count: 77
    .symbol:         _Z8fwd_mega4Args.kd
    .uniform_work_group_size: 1
    .uses_dynamic_stack: false
    .vgpr_count:     255
    .vgpr_spill_count: 0
    .wavefront_size: 64
